# plus: in-proj V-transposed epilogue rewritten by hand (4x4 quad transpose via DPP, 32 eight-byte stores per wave instead of 128 two-byte stores)
# baseline (speedup 1.0000x reference)
; __device__ __forceinline__ unsigned f2bf(float f) { return pk2(f, 0.f) & 0xffffu; }
;     __device__ __forceinline__ void operator()(const f32x4 (&acc)[2][2][4][2], const pg8::Unit& u, int wr, int wc, int fr, int fq) const {
;     ...
;         } else if (seg == 7) {
;             bf16* VT = (bf16*)(ws + WS_VN);
;             EPI_LOOP_BEGIN
;                 const int c = col - 7 * WA; const int hh = c >> 7, d = c & 127;
;                 int bb, tok; if (row < ML) { bb = row / SEQ; tok = row % SEQ; } else { bb = (row - ML) / CTX; tok = SEQ + (row - ML) % CTX; }
;                 bf16* o = VT + ((size_t)(bb * NHEAD + hh) * HD + d) * VT_PITCH + tok;
;                 o[0] = (bf16)f2bf(v.x); o[VT_PITCH] = (bf16)f2bf(v.y); o[2 * VT_PITCH] = (bf16)f2bf(v.z); o[3 * VT_PITCH] = (bf16)f2bf(v.w);
;             EPI_LOOP_END
.LBB0_205:
	s_andn2_b64 vcc, exec, s[6:7]
	s_cbranch_vccnz .LBB0_207
	s_lshr_b32 s6, s64, 3
	s_and_b32 s7, s64, 7
	s_lshl_b32 s7, s7, 8
	s_sub_i32 s68, s64, 32
	s_cmp_lt_u32 s64, 32
	s_cselect_b32 s6, s6, s68
	s_cselect_b32 s7, s7, 0x800
	s_and_b32 s68, s66, 3
	s_lshl_b32 s68, s68, 1
	s_lshl_b32 s6, s6, 3
	s_add_i32 s6, s6, s68
	s_lshl_b32 s6, s6, 7
	s_add_i32 s6, s6, s85
	s_add_i32 s7, s7, s84
	v_and_b32_e32 v150, 3, v225
	v_lshrrev_b32_e32 v151, 2, v225
	v_lshl_add_u32 v152, v226, 2, v150
	v_add_u32_e32 v152, s6, v152
	v_lshl_add_u32 v153, v151, 2, s7
	v_mul_u32_u24_e32 v154, 0x1200, v152
	v_lshl_add_u32 v156, v153, 1, v154
	v_add_u32_e32 v157, 0x12000, v156
	v_add_u32_e32 v158, 0x90000, v156
	v_add_u32_e32 v159, 0xa2000, v156
	v_and_b32_e32 v160, 1, v225
	v_and_b32_e32 v161, 2, v225
	v_cmp_ne_u32_e64 s[38:39], 0, v160
	v_cmp_ne_u32_e64 s[40:41], 0, v161
	s_nop 0
	v_cndmask_b32_e64 v162, v125, v124, s[38:39]
	v_cndmask_b32_e64 v163, v127, v126, s[38:39]
	v_cndmask_b32_e64 v170, v121, v120, s[38:39]
	v_cndmask_b32_e64 v171, v123, v122, s[38:39]
	v_mov_b32_dpp v164, v162 quad_perm:[1,0,3,2] row_mask:0xf bank_mask:0xf
	v_mov_b32_dpp v165, v163 quad_perm:[1,0,3,2] row_mask:0xf bank_mask:0xf
	v_mov_b32_dpp v172, v170 quad_perm:[1,0,3,2] row_mask:0xf bank_mask:0xf
	v_mov_b32_dpp v173, v171 quad_perm:[1,0,3,2] row_mask:0xf bank_mask:0xf
	v_cndmask_b32_e64 v124, v124, v164, s[38:39]
	v_cndmask_b32_e64 v125, v164, v125, s[38:39]
	v_cndmask_b32_e64 v126, v126, v165, s[38:39]
	v_cndmask_b32_e64 v127, v165, v127, s[38:39]
	v_cndmask_b32_e64 v120, v120, v172, s[38:39]
	v_cndmask_b32_e64 v121, v172, v121, s[38:39]
	v_cndmask_b32_e64 v122, v122, v173, s[38:39]
	v_cndmask_b32_e64 v123, v173, v123, s[38:39]
	v_cndmask_b32_e64 v166, v126, v124, s[40:41]
	v_cndmask_b32_e64 v167, v127, v125, s[40:41]
	v_cndmask_b32_e64 v174, v122, v120, s[40:41]
	v_cndmask_b32_e64 v175, v123, v121, s[40:41]
	v_mov_b32_dpp v168, v166 quad_perm:[2,3,0,1] row_mask:0xf bank_mask:0xf
	v_mov_b32_dpp v169, v167 quad_perm:[2,3,0,1] row_mask:0xf bank_mask:0xf
	v_mov_b32_dpp v176, v174 quad_perm:[2,3,0,1] row_mask:0xf bank_mask:0xf
	v_mov_b32_dpp v177, v175 quad_perm:[2,3,0,1] row_mask:0xf bank_mask:0xf
	v_cndmask_b32_e64 v124, v124, v168, s[40:41]
	v_cndmask_b32_e64 v125, v125, v169, s[40:41]
	v_cndmask_b32_e64 v126, v168, v126, s[40:41]
	v_cndmask_b32_e64 v127, v169, v127, s[40:41]
	v_cndmask_b32_e64 v120, v120, v176, s[40:41]
	v_cndmask_b32_e64 v121, v121, v177, s[40:41]
	v_cndmask_b32_e64 v122, v176, v122, s[40:41]
	v_cndmask_b32_e64 v123, v177, v123, s[40:41]
	v_cvt_pk_bf16_f32 v178, v124, v125
	v_cvt_pk_bf16_f32 v179, v126, v127
	v_cvt_pk_bf16_f32 v180, v120, v121
	v_cvt_pk_bf16_f32 v181, v122, v123
	global_store_dwordx2 v156, v[178:179], s[52:53]
	global_store_dwordx2 v157, v[180:181], s[52:53]
	v_cndmask_b32_e64 v162, v117, v116, s[38:39]
	v_cndmask_b32_e64 v163, v119, v118, s[38:39]
	v_cndmask_b32_e64 v170, v113, v112, s[38:39]
	v_cndmask_b32_e64 v171, v115, v114, s[38:39]
	v_mov_b32_dpp v164, v162 quad_perm:[1,0,3,2] row_mask:0xf bank_mask:0xf
	v_mov_b32_dpp v165, v163 quad_perm:[1,0,3,2] row_mask:0xf bank_mask:0xf
	v_mov_b32_dpp v172, v170 quad_perm:[1,0,3,2] row_mask:0xf bank_mask:0xf
	v_mov_b32_dpp v173, v171 quad_perm:[1,0,3,2] row_mask:0xf bank_mask:0xf
	v_cndmask_b32_e64 v116, v116, v164, s[38:39]
	v_cndmask_b32_e64 v117, v164, v117, s[38:39]
	v_cndmask_b32_e64 v118, v118, v165, s[38:39]
	v_cndmask_b32_e64 v119, v165, v119, s[38:39]
	v_cndmask_b32_e64 v112, v112, v172, s[38:39]
	v_cndmask_b32_e64 v113, v172, v113, s[38:39]
	v_cndmask_b32_e64 v114, v114, v173, s[38:39]
	v_cndmask_b32_e64 v115, v173, v115, s[38:39]
	v_cndmask_b32_e64 v166, v118, v116, s[40:41]
	v_cndmask_b32_e64 v167, v119, v117, s[40:41]
	v_cndmask_b32_e64 v174, v114, v112, s[40:41]
	v_cndmask_b32_e64 v175, v115, v113, s[40:41]
	v_mov_b32_dpp v168, v166 quad_perm:[2,3,0,1] row_mask:0xf bank_mask:0xf
	v_mov_b32_dpp v169, v167 quad_perm:[2,3,0,1] row_mask:0xf bank_mask:0xf
	v_mov_b32_dpp v176, v174 quad_perm:[2,3,0,1] row_mask:0xf bank_mask:0xf
	v_mov_b32_dpp v177, v175 quad_perm:[2,3,0,1] row_mask:0xf bank_mask:0xf
	v_cndmask_b32_e64 v116, v116, v168, s[40:41]
	v_cndmask_b32_e64 v117, v117, v169, s[40:41]
	v_cndmask_b32_e64 v118, v168, v118, s[40:41]
	v_cndmask_b32_e64 v119, v169, v119, s[40:41]
	v_cndmask_b32_e64 v112, v112, v176, s[40:41]
	v_cndmask_b32_e64 v113, v113, v177, s[40:41]
	v_cndmask_b32_e64 v114, v176, v114, s[40:41]
	v_cndmask_b32_e64 v115, v177, v115, s[40:41]
	v_cvt_pk_bf16_f32 v182, v116, v117
	v_cvt_pk_bf16_f32 v183, v118, v119
	v_cvt_pk_bf16_f32 v184, v112, v113
	v_cvt_pk_bf16_f32 v185, v114, v115
	global_store_dwordx2 v158, v[182:183], s[52:53]
	global_store_dwordx2 v159, v[184:185], s[52:53]
	v_cndmask_b32_e64 v162, v109, v108, s[38:39]
	v_cndmask_b32_e64 v163, v111, v110, s[38:39]
	v_cndmask_b32_e64 v170, v105, v104, s[38:39]
	v_cndmask_b32_e64 v171, v107, v106, s[38:39]
	v_mov_b32_dpp v164, v162 quad_perm:[1,0,3,2] row_mask:0xf bank_mask:0xf
	v_mov_b32_dpp v165, v163 quad_perm:[1,0,3,2] row_mask:0xf bank_mask:0xf
	v_mov_b32_dpp v172, v170 quad_perm:[1,0,3,2] row_mask:0xf bank_mask:0xf
	v_mov_b32_dpp v173, v171 quad_perm:[1,0,3,2] row_mask:0xf bank_mask:0xf
	v_cndmask_b32_e64 v108, v108, v164, s[38:39]
	v_cndmask_b32_e64 v109, v164, v109, s[38:39]
	v_cndmask_b32_e64 v110, v110, v165, s[38:39]
	v_cndmask_b32_e64 v111, v165, v111, s[38:39]
	v_cndmask_b32_e64 v104, v104, v172, s[38:39]
	v_cndmask_b32_e64 v105, v172, v105, s[38:39]
	v_cndmask_b32_e64 v106, v106, v173, s[38:39]
	v_cndmask_b32_e64 v107, v173, v107, s[38:39]
	v_cndmask_b32_e64 v166, v110, v108, s[40:41]
; __device__ __forceinline__ unsigned f2bf(float f) { return pk2(f, 0.f) & 0xffffu; }
;     __device__ __forceinline__ void operator()(const f32x4 (&acc)[2][2][4][2], const pg8::Unit& u, int wr, int wc, int fr, int fq) const {
;     ...
;         } else if (seg == 7) {
;             bf16* VT = (bf16*)(ws + WS_VN);
;             EPI_LOOP_BEGIN
;                 const int c = col - 7 * WA; const int hh = c >> 7, d = c & 127;
;                 int bb, tok; if (row < ML) { bb = row / SEQ; tok = row % SEQ; } else { bb = (row - ML) / CTX; tok = SEQ + (row - ML) % CTX; }
;                 bf16* o = VT + ((size_t)(bb * NHEAD + hh) * HD + d) * VT_PITCH + tok;
;                 o[0] = (bf16)f2bf(v.x); o[VT_PITCH] = (bf16)f2bf(v.y); o[2 * VT_PITCH] = (bf16)f2bf(v.z); o[3 * VT_PITCH] = (bf16)f2bf(v.w);
;             EPI_LOOP_END
	v_cndmask_b32_e64 v167, v111, v109, s[40:41]
	v_cndmask_b32_e64 v174, v106, v104, s[40:41]
	v_cndmask_b32_e64 v175, v107, v105, s[40:41]
	v_mov_b32_dpp v168, v166 quad_perm:[2,3,0,1] row_mask:0xf bank_mask:0xf
	v_mov_b32_dpp v169, v167 quad_perm:[2,3,0,1] row_mask:0xf bank_mask:0xf
	v_mov_b32_dpp v176, v174 quad_perm:[2,3,0,1] row_mask:0xf bank_mask:0xf
	v_mov_b32_dpp v177, v175 quad_perm:[2,3,0,1] row_mask:0xf bank_mask:0xf
	v_cndmask_b32_e64 v108, v108, v168, s[40:41]
	v_cndmask_b32_e64 v109, v109, v169, s[40:41]
	v_cndmask_b32_e64 v110, v168, v110, s[40:41]
	v_cndmask_b32_e64 v111, v169, v111, s[40:41]
	v_cndmask_b32_e64 v104, v104, v176, s[40:41]
	v_cndmask_b32_e64 v105, v105, v177, s[40:41]
	v_cndmask_b32_e64 v106, v176, v106, s[40:41]
	v_cndmask_b32_e64 v107, v177, v107, s[40:41]
	v_cvt_pk_bf16_f32 v178, v108, v109
	v_cvt_pk_bf16_f32 v179, v110, v111
	v_cvt_pk_bf16_f32 v180, v104, v105
	v_cvt_pk_bf16_f32 v181, v106, v107
	global_store_dwordx2 v156, v[178:179], s[52:53] offset:32
	global_store_dwordx2 v157, v[180:181], s[52:53] offset:32
	v_cndmask_b32_e64 v162, v101, v100, s[38:39]
	v_cndmask_b32_e64 v163, v103, v102, s[38:39]
	v_cndmask_b32_e64 v170, v97, v96, s[38:39]
	v_cndmask_b32_e64 v171, v99, v98, s[38:39]
	v_mov_b32_dpp v164, v162 quad_perm:[1,0,3,2] row_mask:0xf bank_mask:0xf
	v_mov_b32_dpp v165, v163 quad_perm:[1,0,3,2] row_mask:0xf bank_mask:0xf
	v_mov_b32_dpp v172, v170 quad_perm:[1,0,3,2] row_mask:0xf bank_mask:0xf
	v_mov_b32_dpp v173, v171 quad_perm:[1,0,3,2] row_mask:0xf bank_mask:0xf
	v_cndmask_b32_e64 v100, v100, v164, s[38:39]
	v_cndmask_b32_e64 v101, v164, v101, s[38:39]
	v_cndmask_b32_e64 v102, v102, v165, s[38:39]
	v_cndmask_b32_e64 v103, v165, v103, s[38:39]
	v_cndmask_b32_e64 v96, v96, v172, s[38:39]
	v_cndmask_b32_e64 v97, v172, v97, s[38:39]
	v_cndmask_b32_e64 v98, v98, v173, s[38:39]
	v_cndmask_b32_e64 v99, v173, v99, s[38:39]
	v_cndmask_b32_e64 v166, v102, v100, s[40:41]
	v_cndmask_b32_e64 v167, v103, v101, s[40:41]
	v_cndmask_b32_e64 v174, v98, v96, s[40:41]
	v_cndmask_b32_e64 v175, v99, v97, s[40:41]
	v_mov_b32_dpp v168, v166 quad_perm:[2,3,0,1] row_mask:0xf bank_mask:0xf
	v_mov_b32_dpp v169, v167 quad_perm:[2,3,0,1] row_mask:0xf bank_mask:0xf
	v_mov_b32_dpp v176, v174 quad_perm:[2,3,0,1] row_mask:0xf bank_mask:0xf
	v_mov_b32_dpp v177, v175 quad_perm:[2,3,0,1] row_mask:0xf bank_mask:0xf
	v_cndmask_b32_e64 v100, v100, v168, s[40:41]
	v_cndmask_b32_e64 v101, v101, v169, s[40:41]
	v_cndmask_b32_e64 v102, v168, v102, s[40:41]
	v_cndmask_b32_e64 v103, v169, v103, s[40:41]
	v_cndmask_b32_e64 v96, v96, v176, s[40:41]
	v_cndmask_b32_e64 v97, v97, v177, s[40:41]
	v_cndmask_b32_e64 v98, v176, v98, s[40:41]
	v_cndmask_b32_e64 v99, v177, v99, s[40:41]
	v_cvt_pk_bf16_f32 v182, v100, v101
	v_cvt_pk_bf16_f32 v183, v102, v103
	v_cvt_pk_bf16_f32 v184, v96, v97
	v_cvt_pk_bf16_f32 v185, v98, v99
	global_store_dwordx2 v158, v[182:183], s[52:53] offset:32
	global_store_dwordx2 v159, v[184:185], s[52:53] offset:32
	v_cndmask_b32_e64 v162, v93, v92, s[38:39]
	v_cndmask_b32_e64 v163, v95, v94, s[38:39]
	v_cndmask_b32_e64 v170, v89, v88, s[38:39]
	v_cndmask_b32_e64 v171, v91, v90, s[38:39]
	v_mov_b32_dpp v164, v162 quad_perm:[1,0,3,2] row_mask:0xf bank_mask:0xf
	v_mov_b32_dpp v165, v163 quad_perm:[1,0,3,2] row_mask:0xf bank_mask:0xf
	v_mov_b32_dpp v172, v170 quad_perm:[1,0,3,2] row_mask:0xf bank_mask:0xf
	v_mov_b32_dpp v173, v171 quad_perm:[1,0,3,2] row_mask:0xf bank_mask:0xf
	v_cndmask_b32_e64 v92, v92, v164, s[38:39]
	v_cndmask_b32_e64 v93, v164, v93, s[38:39]
	v_cndmask_b32_e64 v94, v94, v165, s[38:39]
	v_cndmask_b32_e64 v95, v165, v95, s[38:39]
	v_cndmask_b32_e64 v88, v88, v172, s[38:39]
	v_cndmask_b32_e64 v89, v172, v89, s[38:39]
	v_cndmask_b32_e64 v90, v90, v173, s[38:39]
	v_cndmask_b32_e64 v91, v173, v91, s[38:39]
	v_cndmask_b32_e64 v166, v94, v92, s[40:41]
	v_cndmask_b32_e64 v167, v95, v93, s[40:41]
	v_cndmask_b32_e64 v174, v90, v88, s[40:41]
	v_cndmask_b32_e64 v175, v91, v89, s[40:41]
	v_mov_b32_dpp v168, v166 quad_perm:[2,3,0,1] row_mask:0xf bank_mask:0xf
	v_mov_b32_dpp v169, v167 quad_perm:[2,3,0,1] row_mask:0xf bank_mask:0xf
	v_mov_b32_dpp v176, v174 quad_perm:[2,3,0,1] row_mask:0xf bank_mask:0xf
	v_mov_b32_dpp v177, v175 quad_perm:[2,3,0,1] row_mask:0xf bank_mask:0xf
	v_cndmask_b32_e64 v92, v92, v168, s[40:41]
	v_cndmask_b32_e64 v93, v93, v169, s[40:41]
	v_cndmask_b32_e64 v94, v168, v94, s[40:41]
	v_cndmask_b32_e64 v95, v169, v95, s[40:41]
	v_cndmask_b32_e64 v88, v88, v176, s[40:41]
	v_cndmask_b32_e64 v89, v89, v177, s[40:41]
	v_cndmask_b32_e64 v90, v176, v90, s[40:41]
	v_cndmask_b32_e64 v91, v177, v91, s[40:41]
	v_cvt_pk_bf16_f32 v178, v92, v93
	v_cvt_pk_bf16_f32 v179, v94, v95
	v_cvt_pk_bf16_f32 v180, v88, v89
	v_cvt_pk_bf16_f32 v181, v90, v91
	global_store_dwordx2 v156, v[178:179], s[52:53] offset:64
	global_store_dwordx2 v157, v[180:181], s[52:53] offset:64
	v_cndmask_b32_e64 v162, v85, v84, s[38:39]
	v_cndmask_b32_e64 v163, v87, v86, s[38:39]
	v_cndmask_b32_e64 v170, v81, v80, s[38:39]
	v_cndmask_b32_e64 v171, v83, v82, s[38:39]
	v_mov_b32_dpp v164, v162 quad_perm:[1,0,3,2] row_mask:0xf bank_mask:0xf
	v_mov_b32_dpp v165, v163 quad_perm:[1,0,3,2] row_mask:0xf bank_mask:0xf
	v_mov_b32_dpp v172, v170 quad_perm:[1,0,3,2] row_mask:0xf bank_mask:0xf
	v_mov_b32_dpp v173, v171 quad_perm:[1,0,3,2] row_mask:0xf bank_mask:0xf
	v_cndmask_b32_e64 v84, v84, v164, s[38:39]
	v_cndmask_b32_e64 v85, v164, v85, s[38:39]
	v_cndmask_b32_e64 v86, v86, v165, s[38:39]
	v_cndmask_b32_e64 v87, v165, v87, s[38:39]
	v_cndmask_b32_e64 v80, v80, v172, s[38:39]
	v_cndmask_b32_e64 v81, v172, v81, s[38:39]
	v_cndmask_b32_e64 v82, v82, v173, s[38:39]
; __device__ __forceinline__ unsigned f2bf(float f) { return pk2(f, 0.f) & 0xffffu; }
;     __device__ __forceinline__ void operator()(const f32x4 (&acc)[2][2][4][2], const pg8::Unit& u, int wr, int wc, int fr, int fq) const {
;     ...
;         } else if (seg == 7) {
;             bf16* VT = (bf16*)(ws + WS_VN);
;             EPI_LOOP_BEGIN
;                 const int c = col - 7 * WA; const int hh = c >> 7, d = c & 127;
;                 int bb, tok; if (row < ML) { bb = row / SEQ; tok = row % SEQ; } else { bb = (row - ML) / CTX; tok = SEQ + (row - ML) % CTX; }
;                 bf16* o = VT + ((size_t)(bb * NHEAD + hh) * HD + d) * VT_PITCH + tok;
;                 o[0] = (bf16)f2bf(v.x); o[VT_PITCH] = (bf16)f2bf(v.y); o[2 * VT_PITCH] = (bf16)f2bf(v.z); o[3 * VT_PITCH] = (bf16)f2bf(v.w);
;             EPI_LOOP_END
	v_cndmask_b32_e64 v83, v173, v83, s[38:39]
	v_cndmask_b32_e64 v166, v86, v84, s[40:41]
	v_cndmask_b32_e64 v167, v87, v85, s[40:41]
	v_cndmask_b32_e64 v174, v82, v80, s[40:41]
	v_cndmask_b32_e64 v175, v83, v81, s[40:41]
	v_mov_b32_dpp v168, v166 quad_perm:[2,3,0,1] row_mask:0xf bank_mask:0xf
	v_mov_b32_dpp v169, v167 quad_perm:[2,3,0,1] row_mask:0xf bank_mask:0xf
	v_mov_b32_dpp v176, v174 quad_perm:[2,3,0,1] row_mask:0xf bank_mask:0xf
	v_mov_b32_dpp v177, v175 quad_perm:[2,3,0,1] row_mask:0xf bank_mask:0xf
	v_cndmask_b32_e64 v84, v84, v168, s[40:41]
	v_cndmask_b32_e64 v85, v85, v169, s[40:41]
	v_cndmask_b32_e64 v86, v168, v86, s[40:41]
	v_cndmask_b32_e64 v87, v169, v87, s[40:41]
	v_cndmask_b32_e64 v80, v80, v176, s[40:41]
	v_cndmask_b32_e64 v81, v81, v177, s[40:41]
	v_cndmask_b32_e64 v82, v176, v82, s[40:41]
	v_cndmask_b32_e64 v83, v177, v83, s[40:41]
	v_cvt_pk_bf16_f32 v182, v84, v85
	v_cvt_pk_bf16_f32 v183, v86, v87
	v_cvt_pk_bf16_f32 v184, v80, v81
	v_cvt_pk_bf16_f32 v185, v82, v83
	global_store_dwordx2 v158, v[182:183], s[52:53] offset:64
	global_store_dwordx2 v159, v[184:185], s[52:53] offset:64
	v_cndmask_b32_e64 v162, v77, v76, s[38:39]
	v_cndmask_b32_e64 v163, v79, v78, s[38:39]
	v_cndmask_b32_e64 v170, v73, v72, s[38:39]
	v_cndmask_b32_e64 v171, v75, v74, s[38:39]
	v_mov_b32_dpp v164, v162 quad_perm:[1,0,3,2] row_mask:0xf bank_mask:0xf
	v_mov_b32_dpp v165, v163 quad_perm:[1,0,3,2] row_mask:0xf bank_mask:0xf
	v_mov_b32_dpp v172, v170 quad_perm:[1,0,3,2] row_mask:0xf bank_mask:0xf
	v_mov_b32_dpp v173, v171 quad_perm:[1,0,3,2] row_mask:0xf bank_mask:0xf
	v_cndmask_b32_e64 v76, v76, v164, s[38:39]
	v_cndmask_b32_e64 v77, v164, v77, s[38:39]
	v_cndmask_b32_e64 v78, v78, v165, s[38:39]
	v_cndmask_b32_e64 v79, v165, v79, s[38:39]
	v_cndmask_b32_e64 v72, v72, v172, s[38:39]
	v_cndmask_b32_e64 v73, v172, v73, s[38:39]
	v_cndmask_b32_e64 v74, v74, v173, s[38:39]
	v_cndmask_b32_e64 v75, v173, v75, s[38:39]
	v_cndmask_b32_e64 v166, v78, v76, s[40:41]
	v_cndmask_b32_e64 v167, v79, v77, s[40:41]
	v_cndmask_b32_e64 v174, v74, v72, s[40:41]
	v_cndmask_b32_e64 v175, v75, v73, s[40:41]
	v_mov_b32_dpp v168, v166 quad_perm:[2,3,0,1] row_mask:0xf bank_mask:0xf
	v_mov_b32_dpp v169, v167 quad_perm:[2,3,0,1] row_mask:0xf bank_mask:0xf
	v_mov_b32_dpp v176, v174 quad_perm:[2,3,0,1] row_mask:0xf bank_mask:0xf
	v_mov_b32_dpp v177, v175 quad_perm:[2,3,0,1] row_mask:0xf bank_mask:0xf
	v_cndmask_b32_e64 v76, v76, v168, s[40:41]
	v_cndmask_b32_e64 v77, v77, v169, s[40:41]
	v_cndmask_b32_e64 v78, v168, v78, s[40:41]
	v_cndmask_b32_e64 v79, v169, v79, s[40:41]
	v_cndmask_b32_e64 v72, v72, v176, s[40:41]
	v_cndmask_b32_e64 v73, v73, v177, s[40:41]
	v_cndmask_b32_e64 v74, v176, v74, s[40:41]
	v_cndmask_b32_e64 v75, v177, v75, s[40:41]
	v_cvt_pk_bf16_f32 v178, v76, v77
	v_cvt_pk_bf16_f32 v179, v78, v79
	v_cvt_pk_bf16_f32 v180, v72, v73
	v_cvt_pk_bf16_f32 v181, v74, v75
	global_store_dwordx2 v156, v[178:179], s[52:53] offset:96
	global_store_dwordx2 v157, v[180:181], s[52:53] offset:96
	v_cndmask_b32_e64 v162, v69, v68, s[38:39]
	v_cndmask_b32_e64 v163, v71, v70, s[38:39]
	v_cndmask_b32_e64 v170, v65, v64, s[38:39]
	v_cndmask_b32_e64 v171, v67, v66, s[38:39]
	v_mov_b32_dpp v164, v162 quad_perm:[1,0,3,2] row_mask:0xf bank_mask:0xf
	v_mov_b32_dpp v165, v163 quad_perm:[1,0,3,2] row_mask:0xf bank_mask:0xf
	v_mov_b32_dpp v172, v170 quad_perm:[1,0,3,2] row_mask:0xf bank_mask:0xf
	v_mov_b32_dpp v173, v171 quad_perm:[1,0,3,2] row_mask:0xf bank_mask:0xf
	v_cndmask_b32_e64 v68, v68, v164, s[38:39]
	v_cndmask_b32_e64 v69, v164, v69, s[38:39]
	v_cndmask_b32_e64 v70, v70, v165, s[38:39]
	v_cndmask_b32_e64 v71, v165, v71, s[38:39]
	v_cndmask_b32_e64 v64, v64, v172, s[38:39]
	v_cndmask_b32_e64 v65, v172, v65, s[38:39]
	v_cndmask_b32_e64 v66, v66, v173, s[38:39]
	v_cndmask_b32_e64 v67, v173, v67, s[38:39]
	v_cndmask_b32_e64 v166, v70, v68, s[40:41]
	v_cndmask_b32_e64 v167, v71, v69, s[40:41]
	v_cndmask_b32_e64 v174, v66, v64, s[40:41]
	v_cndmask_b32_e64 v175, v67, v65, s[40:41]
	v_mov_b32_dpp v168, v166 quad_perm:[2,3,0,1] row_mask:0xf bank_mask:0xf
	v_mov_b32_dpp v169, v167 quad_perm:[2,3,0,1] row_mask:0xf bank_mask:0xf
	v_mov_b32_dpp v176, v174 quad_perm:[2,3,0,1] row_mask:0xf bank_mask:0xf
	v_mov_b32_dpp v177, v175 quad_perm:[2,3,0,1] row_mask:0xf bank_mask:0xf
	v_cndmask_b32_e64 v68, v68, v168, s[40:41]
	v_cndmask_b32_e64 v69, v69, v169, s[40:41]
	v_cndmask_b32_e64 v70, v168, v70, s[40:41]
	v_cndmask_b32_e64 v71, v169, v71, s[40:41]
	v_cndmask_b32_e64 v64, v64, v176, s[40:41]
	v_cndmask_b32_e64 v65, v65, v177, s[40:41]
	v_cndmask_b32_e64 v66, v176, v66, s[40:41]
	v_cndmask_b32_e64 v67, v177, v67, s[40:41]
	v_cvt_pk_bf16_f32 v182, v68, v69
	v_cvt_pk_bf16_f32 v183, v70, v71
	v_cvt_pk_bf16_f32 v184, v64, v65
	v_cvt_pk_bf16_f32 v185, v66, v67
	global_store_dwordx2 v158, v[182:183], s[52:53] offset:96
	global_store_dwordx2 v159, v[184:185], s[52:53] offset:96
	v_cndmask_b32_e64 v162, v61, v60, s[38:39]
	v_cndmask_b32_e64 v163, v63, v62, s[38:39]
	v_cndmask_b32_e64 v170, v57, v56, s[38:39]
	v_cndmask_b32_e64 v171, v59, v58, s[38:39]
	v_mov_b32_dpp v164, v162 quad_perm:[1,0,3,2] row_mask:0xf bank_mask:0xf
	v_mov_b32_dpp v165, v163 quad_perm:[1,0,3,2] row_mask:0xf bank_mask:0xf
	v_mov_b32_dpp v172, v170 quad_perm:[1,0,3,2] row_mask:0xf bank_mask:0xf
	v_mov_b32_dpp v173, v171 quad_perm:[1,0,3,2] row_mask:0xf bank_mask:0xf
	v_cndmask_b32_e64 v60, v60, v164, s[38:39]
	v_cndmask_b32_e64 v61, v164, v61, s[38:39]
	v_cndmask_b32_e64 v62, v62, v165, s[38:39]
	v_cndmask_b32_e64 v63, v165, v63, s[38:39]
	v_cndmask_b32_e64 v56, v56, v172, s[38:39]
	v_cndmask_b32_e64 v57, v172, v57, s[38:39]
; __device__ __forceinline__ unsigned f2bf(float f) { return pk2(f, 0.f) & 0xffffu; }
;     __device__ __forceinline__ void operator()(const f32x4 (&acc)[2][2][4][2], const pg8::Unit& u, int wr, int wc, int fr, int fq) const {
;     ...
;             bf16* VT = (bf16*)(ws + WS_VN);
;             EPI_LOOP_BEGIN
;                 const int c = col - 7 * WA; const int hh = c >> 7, d = c & 127;
;                 int bb, tok; if (row < ML) { bb = row / SEQ; tok = row % SEQ; } else { bb = (row - ML) / CTX; tok = SEQ + (row - ML) % CTX; }
;                 bf16* o = VT + ((size_t)(bb * NHEAD + hh) * HD + d) * VT_PITCH + tok;
;                 o[0] = (bf16)f2bf(v.x); o[VT_PITCH] = (bf16)f2bf(v.y); o[2 * VT_PITCH] = (bf16)f2bf(v.z); o[3 * VT_PITCH] = (bf16)f2bf(v.w);
;             EPI_LOOP_END
	v_cndmask_b32_e64 v58, v58, v173, s[38:39]
	v_cndmask_b32_e64 v59, v173, v59, s[38:39]
	v_cndmask_b32_e64 v166, v62, v60, s[40:41]
	v_cndmask_b32_e64 v167, v63, v61, s[40:41]
	v_cndmask_b32_e64 v174, v58, v56, s[40:41]
	v_cndmask_b32_e64 v175, v59, v57, s[40:41]
	v_mov_b32_dpp v168, v166 quad_perm:[2,3,0,1] row_mask:0xf bank_mask:0xf
	v_mov_b32_dpp v169, v167 quad_perm:[2,3,0,1] row_mask:0xf bank_mask:0xf
	v_mov_b32_dpp v176, v174 quad_perm:[2,3,0,1] row_mask:0xf bank_mask:0xf
	v_mov_b32_dpp v177, v175 quad_perm:[2,3,0,1] row_mask:0xf bank_mask:0xf
	v_cndmask_b32_e64 v60, v60, v168, s[40:41]
	v_cndmask_b32_e64 v61, v61, v169, s[40:41]
	v_cndmask_b32_e64 v62, v168, v62, s[40:41]
	v_cndmask_b32_e64 v63, v169, v63, s[40:41]
	v_cndmask_b32_e64 v56, v56, v176, s[40:41]
	v_cndmask_b32_e64 v57, v57, v177, s[40:41]
	v_cndmask_b32_e64 v58, v176, v58, s[40:41]
	v_cndmask_b32_e64 v59, v177, v59, s[40:41]
	v_cvt_pk_bf16_f32 v178, v60, v61
	v_cvt_pk_bf16_f32 v179, v62, v63
	v_cvt_pk_bf16_f32 v180, v56, v57
	v_cvt_pk_bf16_f32 v181, v58, v59
	global_store_dwordx2 v156, v[178:179], s[52:53] offset:256
	global_store_dwordx2 v157, v[180:181], s[52:53] offset:256
	v_cndmask_b32_e64 v162, v53, v52, s[38:39]
	v_cndmask_b32_e64 v163, v55, v54, s[38:39]
	v_cndmask_b32_e64 v170, v49, v48, s[38:39]
	v_cndmask_b32_e64 v171, v51, v50, s[38:39]
	v_mov_b32_dpp v164, v162 quad_perm:[1,0,3,2] row_mask:0xf bank_mask:0xf
	v_mov_b32_dpp v165, v163 quad_perm:[1,0,3,2] row_mask:0xf bank_mask:0xf
	v_mov_b32_dpp v172, v170 quad_perm:[1,0,3,2] row_mask:0xf bank_mask:0xf
	v_mov_b32_dpp v173, v171 quad_perm:[1,0,3,2] row_mask:0xf bank_mask:0xf
	v_cndmask_b32_e64 v52, v52, v164, s[38:39]
	v_cndmask_b32_e64 v53, v164, v53, s[38:39]
	v_cndmask_b32_e64 v54, v54, v165, s[38:39]
	v_cndmask_b32_e64 v55, v165, v55, s[38:39]
	v_cndmask_b32_e64 v48, v48, v172, s[38:39]
	v_cndmask_b32_e64 v49, v172, v49, s[38:39]
	v_cndmask_b32_e64 v50, v50, v173, s[38:39]
	v_cndmask_b32_e64 v51, v173, v51, s[38:39]
	v_cndmask_b32_e64 v166, v54, v52, s[40:41]
	v_cndmask_b32_e64 v167, v55, v53, s[40:41]
	v_cndmask_b32_e64 v174, v50, v48, s[40:41]
	v_cndmask_b32_e64 v175, v51, v49, s[40:41]
	v_mov_b32_dpp v168, v166 quad_perm:[2,3,0,1] row_mask:0xf bank_mask:0xf
	v_mov_b32_dpp v169, v167 quad_perm:[2,3,0,1] row_mask:0xf bank_mask:0xf
	v_mov_b32_dpp v176, v174 quad_perm:[2,3,0,1] row_mask:0xf bank_mask:0xf
	v_mov_b32_dpp v177, v175 quad_perm:[2,3,0,1] row_mask:0xf bank_mask:0xf
	v_cndmask_b32_e64 v52, v52, v168, s[40:41]
	v_cndmask_b32_e64 v53, v53, v169, s[40:41]
	v_cndmask_b32_e64 v54, v168, v54, s[40:41]
	v_cndmask_b32_e64 v55, v169, v55, s[40:41]
	v_cndmask_b32_e64 v48, v48, v176, s[40:41]
	v_cndmask_b32_e64 v49, v49, v177, s[40:41]
	v_cndmask_b32_e64 v50, v176, v50, s[40:41]
	v_cndmask_b32_e64 v51, v177, v51, s[40:41]
	v_cvt_pk_bf16_f32 v182, v52, v53
	v_cvt_pk_bf16_f32 v183, v54, v55
	v_cvt_pk_bf16_f32 v184, v48, v49
	v_cvt_pk_bf16_f32 v185, v50, v51
	global_store_dwordx2 v158, v[182:183], s[52:53] offset:256
	global_store_dwordx2 v159, v[184:185], s[52:53] offset:256
	v_cndmask_b32_e64 v162, v45, v44, s[38:39]
	v_cndmask_b32_e64 v163, v47, v46, s[38:39]
	v_cndmask_b32_e64 v170, v41, v40, s[38:39]
	v_cndmask_b32_e64 v171, v43, v42, s[38:39]
	v_mov_b32_dpp v164, v162 quad_perm:[1,0,3,2] row_mask:0xf bank_mask:0xf
	v_mov_b32_dpp v165, v163 quad_perm:[1,0,3,2] row_mask:0xf bank_mask:0xf
	v_mov_b32_dpp v172, v170 quad_perm:[1,0,3,2] row_mask:0xf bank_mask:0xf
	v_mov_b32_dpp v173, v171 quad_perm:[1,0,3,2] row_mask:0xf bank_mask:0xf
	v_cndmask_b32_e64 v44, v44, v164, s[38:39]
	v_cndmask_b32_e64 v45, v164, v45, s[38:39]
	v_cndmask_b32_e64 v46, v46, v165, s[38:39]
	v_cndmask_b32_e64 v47, v165, v47, s[38:39]
	v_cndmask_b32_e64 v40, v40, v172, s[38:39]
	v_cndmask_b32_e64 v41, v172, v41, s[38:39]
	v_cndmask_b32_e64 v42, v42, v173, s[38:39]
	v_cndmask_b32_e64 v43, v173, v43, s[38:39]
	v_cndmask_b32_e64 v166, v46, v44, s[40:41]
	v_cndmask_b32_e64 v167, v47, v45, s[40:41]
	v_cndmask_b32_e64 v174, v42, v40, s[40:41]
	v_cndmask_b32_e64 v175, v43, v41, s[40:41]
	v_mov_b32_dpp v168, v166 quad_perm:[2,3,0,1] row_mask:0xf bank_mask:0xf
	v_mov_b32_dpp v169, v167 quad_perm:[2,3,0,1] row_mask:0xf bank_mask:0xf
	v_mov_b32_dpp v176, v174 quad_perm:[2,3,0,1] row_mask:0xf bank_mask:0xf
	v_mov_b32_dpp v177, v175 quad_perm:[2,3,0,1] row_mask:0xf bank_mask:0xf
	v_cndmask_b32_e64 v44, v44, v168, s[40:41]
	v_cndmask_b32_e64 v45, v45, v169, s[40:41]
	v_cndmask_b32_e64 v46, v168, v46, s[40:41]
	v_cndmask_b32_e64 v47, v169, v47, s[40:41]
	v_cndmask_b32_e64 v40, v40, v176, s[40:41]
	v_cndmask_b32_e64 v41, v41, v177, s[40:41]
	v_cndmask_b32_e64 v42, v176, v42, s[40:41]
	v_cndmask_b32_e64 v43, v177, v43, s[40:41]
	v_cvt_pk_bf16_f32 v178, v44, v45
	v_cvt_pk_bf16_f32 v179, v46, v47
	v_cvt_pk_bf16_f32 v180, v40, v41
	v_cvt_pk_bf16_f32 v181, v42, v43
	global_store_dwordx2 v156, v[178:179], s[52:53] offset:288
	global_store_dwordx2 v157, v[180:181], s[52:53] offset:288
	v_cndmask_b32_e64 v162, v37, v36, s[38:39]
	v_cndmask_b32_e64 v163, v39, v38, s[38:39]
	v_cndmask_b32_e64 v170, v33, v32, s[38:39]
	v_cndmask_b32_e64 v171, v35, v34, s[38:39]
	v_mov_b32_dpp v164, v162 quad_perm:[1,0,3,2] row_mask:0xf bank_mask:0xf
	v_mov_b32_dpp v165, v163 quad_perm:[1,0,3,2] row_mask:0xf bank_mask:0xf
	v_mov_b32_dpp v172, v170 quad_perm:[1,0,3,2] row_mask:0xf bank_mask:0xf
	v_mov_b32_dpp v173, v171 quad_perm:[1,0,3,2] row_mask:0xf bank_mask:0xf
	v_cndmask_b32_e64 v36, v36, v164, s[38:39]
	v_cndmask_b32_e64 v37, v164, v37, s[38:39]
	v_cndmask_b32_e64 v38, v38, v165, s[38:39]
	v_cndmask_b32_e64 v39, v165, v39, s[38:39]
	v_cndmask_b32_e64 v32, v32, v172, s[38:39]
; __device__ __forceinline__ unsigned f2bf(float f) { return pk2(f, 0.f) & 0xffffu; }
;     __device__ __forceinline__ void operator()(const f32x4 (&acc)[2][2][4][2], const pg8::Unit& u, int wr, int wc, int fr, int fq) const {
;     ...
;             bf16* VT = (bf16*)(ws + WS_VN);
;             EPI_LOOP_BEGIN
;                 const int c = col - 7 * WA; const int hh = c >> 7, d = c & 127;
;                 int bb, tok; if (row < ML) { bb = row / SEQ; tok = row % SEQ; } else { bb = (row - ML) / CTX; tok = SEQ + (row - ML) % CTX; }
;                 bf16* o = VT + ((size_t)(bb * NHEAD + hh) * HD + d) * VT_PITCH + tok;
;                 o[0] = (bf16)f2bf(v.x); o[VT_PITCH] = (bf16)f2bf(v.y); o[2 * VT_PITCH] = (bf16)f2bf(v.z); o[3 * VT_PITCH] = (bf16)f2bf(v.w);
;             EPI_LOOP_END
	v_cndmask_b32_e64 v33, v172, v33, s[38:39]
	v_cndmask_b32_e64 v34, v34, v173, s[38:39]
	v_cndmask_b32_e64 v35, v173, v35, s[38:39]
	v_cndmask_b32_e64 v166, v38, v36, s[40:41]
	v_cndmask_b32_e64 v167, v39, v37, s[40:41]
	v_cndmask_b32_e64 v174, v34, v32, s[40:41]
	v_cndmask_b32_e64 v175, v35, v33, s[40:41]
	v_mov_b32_dpp v168, v166 quad_perm:[2,3,0,1] row_mask:0xf bank_mask:0xf
	v_mov_b32_dpp v169, v167 quad_perm:[2,3,0,1] row_mask:0xf bank_mask:0xf
	v_mov_b32_dpp v176, v174 quad_perm:[2,3,0,1] row_mask:0xf bank_mask:0xf
	v_mov_b32_dpp v177, v175 quad_perm:[2,3,0,1] row_mask:0xf bank_mask:0xf
	v_cndmask_b32_e64 v36, v36, v168, s[40:41]
	v_cndmask_b32_e64 v37, v37, v169, s[40:41]
	v_cndmask_b32_e64 v38, v168, v38, s[40:41]
	v_cndmask_b32_e64 v39, v169, v39, s[40:41]
	v_cndmask_b32_e64 v32, v32, v176, s[40:41]
	v_cndmask_b32_e64 v33, v33, v177, s[40:41]
	v_cndmask_b32_e64 v34, v176, v34, s[40:41]
	v_cndmask_b32_e64 v35, v177, v35, s[40:41]
	v_cvt_pk_bf16_f32 v182, v36, v37
	v_cvt_pk_bf16_f32 v183, v38, v39
	v_cvt_pk_bf16_f32 v184, v32, v33
	v_cvt_pk_bf16_f32 v185, v34, v35
	global_store_dwordx2 v158, v[182:183], s[52:53] offset:288
	global_store_dwordx2 v159, v[184:185], s[52:53] offset:288
	v_cndmask_b32_e64 v162, v29, v28, s[38:39]
	v_cndmask_b32_e64 v163, v31, v30, s[38:39]
	v_cndmask_b32_e64 v170, v25, v24, s[38:39]
	v_cndmask_b32_e64 v171, v27, v26, s[38:39]
	v_mov_b32_dpp v164, v162 quad_perm:[1,0,3,2] row_mask:0xf bank_mask:0xf
	v_mov_b32_dpp v165, v163 quad_perm:[1,0,3,2] row_mask:0xf bank_mask:0xf
	v_mov_b32_dpp v172, v170 quad_perm:[1,0,3,2] row_mask:0xf bank_mask:0xf
	v_mov_b32_dpp v173, v171 quad_perm:[1,0,3,2] row_mask:0xf bank_mask:0xf
	v_cndmask_b32_e64 v28, v28, v164, s[38:39]
	v_cndmask_b32_e64 v29, v164, v29, s[38:39]
	v_cndmask_b32_e64 v30, v30, v165, s[38:39]
	v_cndmask_b32_e64 v31, v165, v31, s[38:39]
	v_cndmask_b32_e64 v24, v24, v172, s[38:39]
	v_cndmask_b32_e64 v25, v172, v25, s[38:39]
	v_cndmask_b32_e64 v26, v26, v173, s[38:39]
	v_cndmask_b32_e64 v27, v173, v27, s[38:39]
	v_cndmask_b32_e64 v166, v30, v28, s[40:41]
	v_cndmask_b32_e64 v167, v31, v29, s[40:41]
	v_cndmask_b32_e64 v174, v26, v24, s[40:41]
	v_cndmask_b32_e64 v175, v27, v25, s[40:41]
	v_mov_b32_dpp v168, v166 quad_perm:[2,3,0,1] row_mask:0xf bank_mask:0xf
	v_mov_b32_dpp v169, v167 quad_perm:[2,3,0,1] row_mask:0xf bank_mask:0xf
	v_mov_b32_dpp v176, v174 quad_perm:[2,3,0,1] row_mask:0xf bank_mask:0xf
	v_mov_b32_dpp v177, v175 quad_perm:[2,3,0,1] row_mask:0xf bank_mask:0xf
	v_cndmask_b32_e64 v28, v28, v168, s[40:41]
	v_cndmask_b32_e64 v29, v29, v169, s[40:41]
	v_cndmask_b32_e64 v30, v168, v30, s[40:41]
	v_cndmask_b32_e64 v31, v169, v31, s[40:41]
	v_cndmask_b32_e64 v24, v24, v176, s[40:41]
	v_cndmask_b32_e64 v25, v25, v177, s[40:41]
	v_cndmask_b32_e64 v26, v176, v26, s[40:41]
	v_cndmask_b32_e64 v27, v177, v27, s[40:41]
	v_cvt_pk_bf16_f32 v178, v28, v29
	v_cvt_pk_bf16_f32 v179, v30, v31
	v_cvt_pk_bf16_f32 v180, v24, v25
	v_cvt_pk_bf16_f32 v181, v26, v27
	global_store_dwordx2 v156, v[178:179], s[52:53] offset:320
	global_store_dwordx2 v157, v[180:181], s[52:53] offset:320
	v_cndmask_b32_e64 v162, v21, v20, s[38:39]
	v_cndmask_b32_e64 v163, v23, v22, s[38:39]
	v_cndmask_b32_e64 v170, v17, v16, s[38:39]
	v_cndmask_b32_e64 v171, v19, v18, s[38:39]
	v_mov_b32_dpp v164, v162 quad_perm:[1,0,3,2] row_mask:0xf bank_mask:0xf
	v_mov_b32_dpp v165, v163 quad_perm:[1,0,3,2] row_mask:0xf bank_mask:0xf
	v_mov_b32_dpp v172, v170 quad_perm:[1,0,3,2] row_mask:0xf bank_mask:0xf
	v_mov_b32_dpp v173, v171 quad_perm:[1,0,3,2] row_mask:0xf bank_mask:0xf
	v_cndmask_b32_e64 v20, v20, v164, s[38:39]
	v_cndmask_b32_e64 v21, v164, v21, s[38:39]
	v_cndmask_b32_e64 v22, v22, v165, s[38:39]
	v_cndmask_b32_e64 v23, v165, v23, s[38:39]
	v_cndmask_b32_e64 v16, v16, v172, s[38:39]
	v_cndmask_b32_e64 v17, v172, v17, s[38:39]
	v_cndmask_b32_e64 v18, v18, v173, s[38:39]
	v_cndmask_b32_e64 v19, v173, v19, s[38:39]
	v_cndmask_b32_e64 v166, v22, v20, s[40:41]
	v_cndmask_b32_e64 v167, v23, v21, s[40:41]
	v_cndmask_b32_e64 v174, v18, v16, s[40:41]
	v_cndmask_b32_e64 v175, v19, v17, s[40:41]
	v_mov_b32_dpp v168, v166 quad_perm:[2,3,0,1] row_mask:0xf bank_mask:0xf
	v_mov_b32_dpp v169, v167 quad_perm:[2,3,0,1] row_mask:0xf bank_mask:0xf
	v_mov_b32_dpp v176, v174 quad_perm:[2,3,0,1] row_mask:0xf bank_mask:0xf
	v_mov_b32_dpp v177, v175 quad_perm:[2,3,0,1] row_mask:0xf bank_mask:0xf
; __device__ __forceinline__ unsigned f2bf(float f) { return pk2(f, 0.f) & 0xffffu; }
;     __device__ __forceinline__ void operator()(const f32x4 (&acc)[2][2][4][2], const pg8::Unit& u, int wr, int wc, int fr, int fq) const {
;     ...
;             bf16* VT = (bf16*)(ws + WS_VN);
;             EPI_LOOP_BEGIN
;                 const int c = col - 7 * WA; const int hh = c >> 7, d = c & 127;
;                 int bb, tok; if (row < ML) { bb = row / SEQ; tok = row % SEQ; } else { bb = (row - ML) / CTX; tok = SEQ + (row - ML) % CTX; }
;                 bf16* o = VT + ((size_t)(bb * NHEAD + hh) * HD + d) * VT_PITCH + tok;
;                 o[0] = (bf16)f2bf(v.x); o[VT_PITCH] = (bf16)f2bf(v.y); o[2 * VT_PITCH] = (bf16)f2bf(v.z); o[3 * VT_PITCH] = (bf16)f2bf(v.w);
;             EPI_LOOP_END
	v_cndmask_b32_e64 v20, v20, v168, s[40:41]
	v_cndmask_b32_e64 v21, v21, v169, s[40:41]
	v_cndmask_b32_e64 v22, v168, v22, s[40:41]
	v_cndmask_b32_e64 v23, v169, v23, s[40:41]
	v_cndmask_b32_e64 v16, v16, v176, s[40:41]
	v_cndmask_b32_e64 v17, v17, v177, s[40:41]
	v_cndmask_b32_e64 v18, v176, v18, s[40:41]
	v_cndmask_b32_e64 v19, v177, v19, s[40:41]
	v_cvt_pk_bf16_f32 v182, v20, v21
	v_cvt_pk_bf16_f32 v183, v22, v23
	v_cvt_pk_bf16_f32 v184, v16, v17
	v_cvt_pk_bf16_f32 v185, v18, v19
	global_store_dwordx2 v158, v[182:183], s[52:53] offset:320
	global_store_dwordx2 v159, v[184:185], s[52:53] offset:320
	v_cndmask_b32_e64 v162, v13, v12, s[38:39]
	v_cndmask_b32_e64 v163, v15, v14, s[38:39]
	v_cndmask_b32_e64 v170, v9, v8, s[38:39]
	v_cndmask_b32_e64 v171, v11, v10, s[38:39]
	v_mov_b32_dpp v164, v162 quad_perm:[1,0,3,2] row_mask:0xf bank_mask:0xf
	v_mov_b32_dpp v165, v163 quad_perm:[1,0,3,2] row_mask:0xf bank_mask:0xf
	v_mov_b32_dpp v172, v170 quad_perm:[1,0,3,2] row_mask:0xf bank_mask:0xf
	v_mov_b32_dpp v173, v171 quad_perm:[1,0,3,2] row_mask:0xf bank_mask:0xf
	v_cndmask_b32_e64 v12, v12, v164, s[38:39]
	v_cndmask_b32_e64 v13, v164, v13, s[38:39]
	v_cndmask_b32_e64 v14, v14, v165, s[38:39]
	v_cndmask_b32_e64 v15, v165, v15, s[38:39]
	v_cndmask_b32_e64 v8, v8, v172, s[38:39]
	v_cndmask_b32_e64 v9, v172, v9, s[38:39]
	v_cndmask_b32_e64 v10, v10, v173, s[38:39]
	v_cndmask_b32_e64 v11, v173, v11, s[38:39]
	v_cndmask_b32_e64 v166, v14, v12, s[40:41]
	v_cndmask_b32_e64 v167, v15, v13, s[40:41]
	v_cndmask_b32_e64 v174, v10, v8, s[40:41]
	v_cndmask_b32_e64 v175, v11, v9, s[40:41]
	v_mov_b32_dpp v168, v166 quad_perm:[2,3,0,1] row_mask:0xf bank_mask:0xf
	v_mov_b32_dpp v169, v167 quad_perm:[2,3,0,1] row_mask:0xf bank_mask:0xf
	v_mov_b32_dpp v176, v174 quad_perm:[2,3,0,1] row_mask:0xf bank_mask:0xf
	v_mov_b32_dpp v177, v175 quad_perm:[2,3,0,1] row_mask:0xf bank_mask:0xf
	v_cndmask_b32_e64 v12, v12, v168, s[40:41]
	v_cndmask_b32_e64 v13, v13, v169, s[40:41]
	v_cndmask_b32_e64 v14, v168, v14, s[40:41]
	v_cndmask_b32_e64 v15, v169, v15, s[40:41]
	v_cndmask_b32_e64 v8, v8, v176, s[40:41]
	v_cndmask_b32_e64 v9, v9, v177, s[40:41]
	v_cndmask_b32_e64 v10, v176, v10, s[40:41]
	v_cndmask_b32_e64 v11, v177, v11, s[40:41]
	v_cvt_pk_bf16_f32 v178, v12, v13
	v_cvt_pk_bf16_f32 v179, v14, v15
	v_cvt_pk_bf16_f32 v180, v8, v9
	v_cvt_pk_bf16_f32 v181, v10, v11
	global_store_dwordx2 v156, v[178:179], s[52:53] offset:352
	global_store_dwordx2 v157, v[180:181], s[52:53] offset:352
	v_cndmask_b32_e64 v162, v5, v4, s[38:39]
	v_cndmask_b32_e64 v163, v7, v6, s[38:39]
	v_cndmask_b32_e64 v170, v1, v0, s[38:39]
	v_cndmask_b32_e64 v171, v3, v2, s[38:39]
	v_mov_b32_dpp v164, v162 quad_perm:[1,0,3,2] row_mask:0xf bank_mask:0xf
	v_mov_b32_dpp v165, v163 quad_perm:[1,0,3,2] row_mask:0xf bank_mask:0xf
	v_mov_b32_dpp v172, v170 quad_perm:[1,0,3,2] row_mask:0xf bank_mask:0xf
	v_mov_b32_dpp v173, v171 quad_perm:[1,0,3,2] row_mask:0xf bank_mask:0xf
	v_cndmask_b32_e64 v4, v4, v164, s[38:39]
	v_cndmask_b32_e64 v5, v164, v5, s[38:39]
	v_cndmask_b32_e64 v6, v6, v165, s[38:39]
	v_cndmask_b32_e64 v7, v165, v7, s[38:39]
	v_cndmask_b32_e64 v0, v0, v172, s[38:39]
	v_cndmask_b32_e64 v1, v172, v1, s[38:39]
	v_cndmask_b32_e64 v2, v2, v173, s[38:39]
	v_cndmask_b32_e64 v3, v173, v3, s[38:39]
	v_cndmask_b32_e64 v166, v6, v4, s[40:41]
	v_cndmask_b32_e64 v167, v7, v5, s[40:41]
	v_cndmask_b32_e64 v174, v2, v0, s[40:41]
	v_cndmask_b32_e64 v175, v3, v1, s[40:41]
	v_mov_b32_dpp v168, v166 quad_perm:[2,3,0,1] row_mask:0xf bank_mask:0xf
	v_mov_b32_dpp v169, v167 quad_perm:[2,3,0,1] row_mask:0xf bank_mask:0xf
	v_mov_b32_dpp v176, v174 quad_perm:[2,3,0,1] row_mask:0xf bank_mask:0xf
	v_mov_b32_dpp v177, v175 quad_perm:[2,3,0,1] row_mask:0xf bank_mask:0xf
	v_cndmask_b32_e64 v4, v4, v168, s[40:41]
	v_cndmask_b32_e64 v5, v5, v169, s[40:41]
	v_cndmask_b32_e64 v6, v168, v6, s[40:41]
	v_cndmask_b32_e64 v7, v169, v7, s[40:41]
	v_cndmask_b32_e64 v0, v0, v176, s[40:41]
	v_cndmask_b32_e64 v1, v1, v177, s[40:41]
	v_cndmask_b32_e64 v2, v176, v2, s[40:41]
	v_cndmask_b32_e64 v3, v177, v3, s[40:41]
	v_cvt_pk_bf16_f32 v182, v4, v5
	v_cvt_pk_bf16_f32 v183, v6, v7
	v_cvt_pk_bf16_f32 v184, v0, v1
	v_cvt_pk_bf16_f32 v185, v2, v3
	global_store_dwordx2 v158, v[182:183], s[52:53] offset:352
	global_store_dwordx2 v159, v[184:185], s[52:53] offset:352
